# forget-bias scans (cb_scan) moved from workgroups 0-63 (pass-1 pole) to the idle sample-path workgroups 224-255; plus pipelined chain<0> state update, LN hoist, deferred sample units, batched fold
# speedup vs baseline: 1.0102x; 1.0027x over previous
; #define GSYNC() xcd_barrier(xbar, TIDX(wave) == 0)
; #define cK karg(2)
; #define cV karg(3)
; #define cF karg(4)
; #define S0 karg(5)
; __global__ void __launch_bounds__(512, 2) fwd_kernel(Args args) {
;     ...
;     for (int rep = 0; rep < NREP(2); ++rep) { if (rep) GSYNC(); if (IN(2)) {
;     ...
;         const int mixm = rep ? (REP2_MIX) : (MIX_MASK);
;         if (mixm & 2) { for (int c = bx; c < 64; c += G) attn_body::cb_scan(c >> 3, c & 7, out + O_FP, (float*)(ws + WS_CBG), (char*)lds, wave); }
;         if (mixm & 1) {
;             for (int it = bx; it < 224; it += G) gla::chain<0>((it & 31) >> 2, it & 3, it >> 5, (float*)(ws + WS_SLOC), (float*)(ws + WS_DTOT), QB, KB, VB, OBG, RB, A1, w_a2, b_a2, g_gla, out + O_SP, (char*)lds, wave);
;             if (bx >= 224 || G < 256) {
;                 const int nb = G < 256 ? G : G - 224, b0 = G < 256 ? bx : bx - 224;
;                 if (mixm & 4) { for (int u = b0; u < 64; u += nb) sattn::unit(u >> 3, u & 7, QA, OA, cK, cV, cF, out, (char*)lds, wave); }
;                 if (mixm & 8) { for (int u = b0; u < 32; u += nb) gla::sample_unit(u >> 2, u & 3, QB, KB, VB, OBG, RB, A1, w_a2, b_a2, g_gla, S0, out + O_SS, (char*)lds, wave); } }
;             GSYNC();
;             for (int it = bx; it < 256; it += G) gla::chain<1>((it & 31) >> 2, it & 3, it >> 5, (float*)(ws + WS_SLOC), (float*)(ws + WS_DTOT), QB, KB, VB, OBG, RB, A1, w_a2, b_a2, g_gla, out + O_SP, (char*)lds, wave); }
.LBB0_444:
	s_cmp_lt_i32 s68, 3
	s_cselect_b64 s[22:23], -1, 0
	s_and_b64 s[6:7], s[22:23], s[4:5]
	v_readlane_b32 s14, v246, 14
	s_cmp_lt_u32 s14, 64
	s_cselect_b64 s[84:85], -1, 0
	s_cmp_gt_u32 s14, 63
	v_readlane_b32 s8, v246, 4
	s_cselect_b64 s[4:5], -1, 0
	v_readlane_b32 s9, v246, 5
	s_lshl_b32 s8, s8, 5
	v_writelane_b32 v246, s8, 53
	s_nop 1
	v_writelane_b32 v246, s9, 54
	s_add_u32 s8, s38, 0x4200
	s_addc_u32 s9, s39, 0
	v_writelane_b32 v246, s8, 55
	s_nop 1
	v_writelane_b32 v246, s9, 56
	s_add_u32 s8, s38, 0x4400
	s_addc_u32 s9, s39, 0
	v_writelane_b32 v246, s8, 51
	s_nop 1
	v_writelane_b32 v246, s9, 52
	s_add_u32 s8, s38, 0x4500
	s_addc_u32 s9, s39, 0
	v_writelane_b32 v246, s8, 45
	s_nop 1
	v_writelane_b32 v246, s9, 46
	s_add_u32 s8, s38, 0x4600
	s_addc_u32 s9, s39, 0
	v_writelane_b32 v246, s8, 31
	s_nop 1
	v_writelane_b32 v246, s9, 32
	s_add_u32 s8, s38, 0x4700
	s_addc_u32 s9, s39, 0
	v_writelane_b32 v246, s8, 47
	s_nop 1
	v_writelane_b32 v246, s9, 48
	s_add_u32 s8, s38, 0x4800
	s_addc_u32 s9, s39, 0
	v_writelane_b32 v246, s8, 49
	s_nop 1
	v_writelane_b32 v246, s9, 50
	s_add_u32 s8, s38, 0x4900
	s_addc_u32 s9, s39, 0
	v_writelane_b32 v246, s8, 33
	s_nop 1
	v_writelane_b32 v246, s9, 34
	s_add_u32 s8, s38, 0x4a00
	s_addc_u32 s9, s39, 0
	v_writelane_b32 v246, s8, 35
	s_nop 1
	v_writelane_b32 v246, s9, 36
	s_add_u32 s8, s38, 0x4b00
	s_addc_u32 s9, s39, 0
	v_writelane_b32 v246, s8, 39
	s_nop 1
	v_writelane_b32 v246, s9, 40
	s_add_u32 s8, s38, 0x4c00
	s_addc_u32 s9, s39, 0
	v_writelane_b32 v246, s8, 41
	s_nop 1
	v_writelane_b32 v246, s9, 42
	s_add_u32 s8, s38, 0x4d00
	s_addc_u32 s9, s39, 0
	v_writelane_b32 v246, s8, 37
	s_nop 1
	v_writelane_b32 v246, s9, 38
	s_add_u32 s8, s38, 0x4e00
	s_addc_u32 s9, s39, 0
	v_writelane_b32 v246, s8, 43
	s_nop 1
	v_writelane_b32 v246, s9, 44
	s_add_u32 s8, s38, 0x4f00
	s_addc_u32 s9, s39, 0
	v_writelane_b32 v246, s8, 57
	s_nop 1
	v_writelane_b32 v246, s9, 58
	s_add_u32 s8, s38, 0x5000
	s_addc_u32 s9, s39, 0
	v_writelane_b32 v246, s8, 59
	s_nop 1
	v_writelane_b32 v246, s9, 60
	s_add_u32 s8, s38, 0x5100
	s_addc_u32 s9, s39, 0
	v_writelane_b32 v246, s8, 61
	s_nop 1
	v_writelane_b32 v246, s9, 62
	s_add_u32 s8, s38, 0x5200
	s_addc_u32 s9, s39, 0
	v_writelane_b32 v246, s8, 63
	s_nop 0
	v_readlane_b32 s12, v246, 2
	v_writelane_b32 v245, s9, 0
	s_add_u32 s8, s38, 0x5300
	s_addc_u32 s9, s39, 0
	v_writelane_b32 v245, s8, 1
	s_cmp_eq_u32 s40, 15
	v_readlane_b32 s13, v246, 3
	v_writelane_b32 v245, s9, 2
	s_cselect_b64 s[8:9], -1, 0
	v_writelane_b32 v245, s8, 3
	s_cmp_eq_u32 s40, 14
	s_nop 0
	v_writelane_b32 v245, s9, 4
	s_cselect_b64 s[8:9], -1, 0
	v_writelane_b32 v245, s8, 5
	s_cmp_eq_u32 s40, 13
	s_nop 0
	v_writelane_b32 v245, s9, 6
	s_cselect_b64 s[8:9], -1, 0
	v_writelane_b32 v245, s8, 7
	s_cmp_eq_u32 s40, 12
	s_nop 0
	v_writelane_b32 v245, s9, 8
	s_cselect_b64 s[8:9], -1, 0
	v_writelane_b32 v245, s8, 9
	s_cmp_eq_u32 s40, 11
	s_nop 0
	v_writelane_b32 v245, s9, 10
	s_cselect_b64 s[8:9], -1, 0
	v_writelane_b32 v245, s8, 11
	s_cmp_eq_u32 s40, 10
	s_nop 0
	v_writelane_b32 v245, s9, 12
	s_cselect_b64 s[8:9], -1, 0
	v_writelane_b32 v245, s8, 13
	s_cmp_eq_u32 s40, 9
	s_nop 0
	v_writelane_b32 v245, s9, 14
	s_cselect_b64 s[8:9], -1, 0
	v_writelane_b32 v245, s8, 15
	s_cmp_eq_u32 s40, 8
	s_nop 0
	v_writelane_b32 v245, s9, 16
	s_cselect_b64 s[8:9], -1, 0
	v_writelane_b32 v245, s8, 17
	s_cmp_eq_u32 s40, 7
	s_nop 0
	v_writelane_b32 v245, s9, 18
	s_cselect_b64 s[8:9], -1, 0
	v_writelane_b32 v245, s8, 19
	s_cmp_eq_u32 s40, 6
	s_nop 0
	v_writelane_b32 v245, s9, 20
	s_cselect_b64 s[8:9], -1, 0
	v_writelane_b32 v245, s8, 21
	s_cmp_eq_u32 s40, 5
	s_nop 0
	v_writelane_b32 v245, s9, 22
	s_cselect_b64 s[8:9], -1, 0
	v_writelane_b32 v245, s8, 23
	s_cmp_eq_u32 s40, 4
	s_nop 0
	v_writelane_b32 v245, s9, 24
	s_cselect_b64 s[8:9], -1, 0
	v_writelane_b32 v245, s8, 25
	s_cmp_eq_u32 s40, 3
	s_nop 0
	v_writelane_b32 v245, s9, 26
	s_cselect_b64 s[8:9], -1, 0
	v_writelane_b32 v245, s8, 27
	s_cmp_eq_u32 s40, 2
	s_nop 0
	v_writelane_b32 v245, s9, 28
	s_cselect_b64 s[8:9], -1, 0
	v_writelane_b32 v245, s8, 29
	s_cmp_eq_u32 s40, 1
	s_nop 0
	v_writelane_b32 v245, s9, 30
	s_cselect_b64 s[8:9], -1, 0
	v_writelane_b32 v245, s8, 31
	s_cmp_eq_u32 s40, 0
	s_nop 0
	v_writelane_b32 v245, s9, 32
	s_cselect_b64 s[8:9], -1, 0
	v_writelane_b32 v245, s8, 33
	s_nop 1
	v_writelane_b32 v245, s9, 34
	s_lshl_b32 s8, s40, 8
	s_add_u32 s8, s12, s8
	s_addc_u32 s9, s13, 0
	s_add_u32 s12, s8, 0x1400
	s_addc_u32 s13, s9, 0
	s_add_u32 s8, s8, 0x2400
	s_addc_u32 s9, s9, 0
	v_writelane_b32 v246, s8, 2
	v_writelane_b32 v245, s12, 35
	s_nop 0
	v_writelane_b32 v246, s9, 3
	s_add_u32 s8, s38, 0x7400
	v_writelane_b32 v245, s13, 36
	s_addc_u32 s9, s39, 0
	v_writelane_b32 v245, s8, 37
	s_nop 1
	v_writelane_b32 v245, s9, 38
	s_add_u32 s8, s38, 0x7500
	s_addc_u32 s9, s39, 0
	v_writelane_b32 v245, s8, 39
	s_cmpk_lt_i32 s2, 0x100
	s_nop 0
	v_writelane_b32 v245, s9, 40
	s_cselect_b64 s[8:9], -1, 0
	v_writelane_b32 v245, s8, 41
	s_cmpk_gt_i32 s2, 0xff
	s_nop 0
	v_writelane_b32 v245, s9, 42
	s_cselect_b64 s[8:9], -1, 0
	v_writelane_b32 v245, s8, 43
	s_andn2_b64 vcc, exec, s[6:7]
	s_nop 0
	v_writelane_b32 v245, s9, 44
	s_cbranch_vccnz .LBB0_786
	v_readlane_b32 s6, v246, 4
	s_lshl_b32 s61, s6, 2
	s_add_i32 s10, s61, 0x100
	s_cmpk_gt_u32 s14, 0x7f
	s_cselect_b64 s[38:39], -1, 0
	s_cmpk_gt_u32 s14, 0xbf
	s_cselect_b64 s[40:41], -1, 0
	s_cmpk_gt_u32 s14, 0xff
	s_cselect_b64 s[42:43], -1, 0
	s_cmpk_gt_u32 s14, 0x13f
	s_cselect_b64 s[44:45], -1, 0
	s_cmpk_gt_u32 s14, 0x17f
	s_cselect_b64 s[46:47], -1, 0
	s_cmpk_gt_u32 s14, 0x1bf
	s_cselect_b64 s[48:49], -1, 0
	s_cmpk_gt_u32 s14, 0x1ff
	s_cselect_b64 s[50:51], -1, 0
	v_cndmask_b32_e64 v1, 0, 1, s[4:5]
	v_cndmask_b32_e64 v2, 0, 1, s[38:39]
	s_waitcnt lgkmcnt(0)
	v_cndmask_b32_e64 v3, 0, 1, s[40:41]
	v_cndmask_b32_e64 v4, 0, 1, s[42:43]
	v_cndmask_b32_e64 v5, 0, 1, s[44:45]
	v_cndmask_b32_e64 v6, 0, 1, s[46:47]
	v_cndmask_b32_e64 v7, 0, 1, s[48:49]
	v_cndmask_b32_e64 v8, 0, 1, s[50:51]
	s_cmpk_lt_i32 s2, 0xe0
	v_cmp_ne_u32_e64 s[16:17], 1, v1
	v_cmp_ne_u32_e64 s[90:91], 1, v2
	v_cmp_ne_u32_e64 s[24:25], 1, v3
	v_cmp_ne_u32_e64 s[26:27], 1, v4
	v_cmp_ne_u32_e64 s[28:29], 1, v5
	v_cmp_ne_u32_e64 s[62:63], 1, v6
	v_cmp_ne_u32_e64 s[64:65], 1, v7
	v_cmp_ne_u32_e64 s[66:67], 1, v8
	v_readlane_b32 s7, v246, 5
	s_cbranch_scc1 .LBB0_466
	s_add_i32 s4, s2, 0xffffff20
	s_mov_b32 s5, 0
	s_lshl_b64 s[4:5], s[4:5], 15
	v_mbcnt_lo_u32_b32 v1, -1, 0
	s_add_u32 s4, s4, 0x2d00000
	v_mbcnt_hi_u32_b32 v1, -1, v1
	s_addc_u32 s5, s5, 0
	s_mov_b64 s[6:7], 0x100000
	s_mov_b32 s9, 0
	v_and_b32_e32 v20, 64, v1
	v_add_u32_e32 v21, -1, v1
	v_add_u32_e32 v22, -2, v1
	v_add_u32_e32 v23, -4, v1
	v_add_u32_e32 v24, -8, v1
	v_add_u32_e32 v25, -16, v1
	v_subrev_u32_e32 v26, 32, v1
	s_mov_b32 s14, 0xbfb8aa3b
	v_mov_b32_e32 v27, 0x100
	s_add_i32 s12, s2, 0xffffff20
	s_branch .LBB0_448
; #define lane lane_id_asm()
; __device__ __forceinline__ void cb_scan(int b,int h,const float*__restrict__ logf,float*__restrict__ cbg,char*shm,const int wv){
;     ...
;   _Pragma("unroll") for(int i=0;i<16;++i){ run+=lp[(long)i*NHEAD]; sv[i]=run; }
;   float incl=run;
;   _Pragma("unroll") for(int o_=1;o_<64;o_<<=1){ const float n_=__shfl_up(incl,o_); if(lane>=o_)incl+=n_; }
;   if(lane==63)ws_[wid]=incl;
;   __syncthreads();
;   float wp=0.f; _Pragma("unroll") for(int w_=0;w_<NW;++w_){ const float x_=ws_[w_]; if(w_<wid)wp+=x_; }
;   const float off_=wp+incl-run; float*og=cbg+(long)(b*NHEAD+h)*SEQ+j0;
;   _Pragma("unroll") for(int i=0;i<16;++i) og[i]=-(off_+sv[i])*1.4426950408889634f;
;   __syncthreads();
.LBB0_447:
	v_cmp_gt_u32_e32 vcc, 32, v28
	v_lshl_add_u64 v[2:3], v[2:3], 2, s[68:69]
	s_add_i32 s12, s12, 32
	v_cndmask_b32_e32 v28, v30, v29, vcc
	v_add_f32_e32 v28, v28, v31
	v_sub_f32_e32 v28, v28, v19
	v_lshl_add_u64 v[30:31], v[2:3], 0, s[4:5]
	v_pk_add_f32 v[2:3], v[4:5], v[28:29] op_sel_hi:[1,0]
	v_pk_add_f32 v[4:5], v[6:7], v[28:29] op_sel_hi:[1,0]
	v_pk_mul_f32 v[2:3], v[2:3], s[14:15] op_sel_hi:[1,0]
	v_pk_mul_f32 v[4:5], v[4:5], s[14:15] op_sel_hi:[1,0]
	global_store_dwordx4 v[30:31], v[2:5], off
	s_add_u32 s4, s4, s6
	s_addc_u32 s5, s5, s7
	v_pk_add_f32 v[2:3], v[8:9], v[28:29] op_sel_hi:[1,0]
	v_pk_add_f32 v[4:5], v[10:11], v[28:29] op_sel_hi:[1,0]
	v_pk_mul_f32 v[2:3], v[2:3], s[14:15] op_sel_hi:[1,0]
	v_pk_mul_f32 v[4:5], v[4:5], s[14:15] op_sel_hi:[1,0]
	global_store_dwordx4 v[30:31], v[2:5], off offset:16
	s_cmp_gt_i32 s12, 63
	s_nop 0
	v_pk_add_f32 v[2:3], v[12:13], v[28:29] op_sel_hi:[1,0]
	v_pk_add_f32 v[4:5], v[14:15], v[28:29] op_sel_hi:[1,0]
	v_pk_mul_f32 v[2:3], v[2:3], s[14:15] op_sel_hi:[1,0]
	v_pk_mul_f32 v[4:5], v[4:5], s[14:15] op_sel_hi:[1,0]
	global_store_dwordx4 v[30:31], v[2:5], off offset:32
	s_nop 1
	v_pk_add_f32 v[2:3], v[16:17], v[28:29] op_sel_hi:[1,0]
	v_pk_add_f32 v[4:5], v[18:19], v[28:29] op_sel_hi:[1,0]
	v_pk_mul_f32 v[2:3], v[2:3], s[14:15] op_sel_hi:[1,0]
	v_pk_mul_f32 v[4:5], v[4:5], s[14:15] op_sel_hi:[1,0]
	global_store_dwordx4 v[30:31], v[2:5], off offset:48
	s_barrier
	s_cbranch_scc1 .LBB0_466
